# speedup vs baseline: 1.0063x; 1.0063x over previous
.Lxs_loop0:
	s_sleep 90
	s_sub_u32 s98, s98, 1
	s_cmp_lg_u32 s98, 0
	s_cbranch_scc1 .Lxs_loop0
